# static s_setprio 3 for waves 0-3 in every phase except the chunk scan (adds attention/recurrence pass 1 and pass 2)
# speedup vs baseline: 1.0030x; 1.0028x over previous
.LBB0_24:
	s_mov_b32 s72, s34
	v_readlane_b32 s20, v254, 0
	s_cmp_lg_u32 s70, 0
	s_mov_b64 s[2:3], -1
	s_cbranch_scc0 .LBB0_477
	s_add_i32 s2, s70, -1
	s_mul_hi_i32 s3, s2, 0x92492493
	s_add_i32 s3, s3, s2
	s_lshr_b32 s4, s3, 31
	s_ashr_i32 s3, s3, 2
	s_add_i32 s24, s3, s4
	s_mul_i32 s3, s24, 7
	s_sub_i32 s11, s2, s3
	s_setprio 0
	s_cmp_eq_u32 s11, 2
	s_cbranch_scc1 .Lsp_done
